# v33 + gMLP task prologue: second load group issued before the first group's wait (one round trip less per task)
# baseline (speedup 1.0000x reference)
.LBB0_468:
	s_mov_b64 s[2:3], s[0:1]
	v_mov_b32_e32 v62, v252
	s_load_dwordx2 s[10:11], s[2:3], 0xc0
	s_and_b32 s15, s4, 7
	s_lshl_b32 s5, s4, 4
	v_lshlrev_b32_e32 v22, 4, v62
	v_lshlrev_b32_e32 v4, 3, v62
	s_waitcnt lgkmcnt(0)
	s_add_u32 s12, s10, s84
	s_addc_u32 s13, s11, 0
	s_lshl_b32 s16, s15, 15
	s_add_u32 s12, s12, s16
	s_addc_u32 s13, s13, 0
	v_and_b32_e32 v0, 0xf0, v22
	v_lshl_add_u64 v[2:3], s[12:13], 0, v[0:1]
	s_mov_b64 s[12:13], 0x9b00000
	v_and_b32_e32 v4, 0xffffff80, v4
	v_lshl_add_u64 v[2:3], v[2:3], 0, s[12:13]
	v_ashrrev_i32_e32 v5, 31, v4
	v_lshl_add_u64 v[6:7], v[4:5], 1, v[2:3]
	global_load_dwordx4 v[18:21], v[6:7], off
	v_add_u32_e32 v6, 0x1000, v4
	v_ashrrev_i32_e32 v7, 31, v6
	v_lshl_add_u64 v[6:7], v[6:7], 1, v[2:3]
	s_and_b32 s5, s5, 0x7f80
	global_load_dwordx4 v[14:17], v[6:7], off
	v_add_u32_e32 v6, 0x2000, v4
	v_add_u32_e32 v4, 0x3000, v4
	s_xor_b32 s5, s5, 0x4000
	v_ashrrev_i32_e32 v64, 2, v62
	v_ashrrev_i32_e32 v7, 31, v6
	v_ashrrev_i32_e32 v5, 31, v4
	v_add_u32_e32 v34, s5, v64
	v_lshl_add_u64 v[6:7], v[6:7], 1, v[2:3]
	v_lshl_add_u64 v[2:3], v[4:5], 1, v[2:3]
	v_ashrrev_i32_e32 v35, 31, v34
	global_load_dwordx4 v[10:13], v[6:7], off
	s_add_u32 s12, s10, 0xf500000
	global_load_dwordx4 v[6:9], v[2:3], off
	v_lshlrev_b64 v[2:3], 6, v[34:35]
	s_addc_u32 s13, s11, 0
	v_lshl_add_u64 v[2:3], s[10:11], 0, v[2:3]
	s_mov_b64 s[10:11], 0xf100000
	v_lshl_add_u64 v[30:31], v[2:3], 0, s[10:11]
	s_mov_b32 s10, 0xf100000
	v_add_co_u32_e32 v2, vcc, s10, v2
	v_and_b32_e32 v65, 48, v22
	s_nop 0
	v_addc_co_u32_e32 v3, vcc, 0, v3, vcc
	global_load_dwordx4 v[66:69], v[2:3], off
	s_nop 0
	global_load_dwordx4 v[70:73], v[30:31], off offset:48
	global_load_dwordx4 v[74:77], v[30:31], off offset:32
	s_nop 0
	global_load_dwordx4 v[78:81], v[30:31], off offset:16
	s_lshl_b32 s34, s15, 7
	v_mov_b64_e32 v[2:3], s[12:13]
	v_mad_i64_i32 v[22:23], s[10:11], v34, s49, v[2:3]
	v_lshl_add_u64 v[22:23], v[22:23], 0, s[34:35]
	v_lshlrev_b32_e32 v0, 1, v65
	v_lshl_add_u64 v[26:27], v[22:23], 0, v[0:1]
	global_load_dwordx4 v[22:25], v[26:27], off offset:2064
	global_load_dwordx4 v[38:41], v[26:27], off offset:2048
	s_load_dwordx4 s[36:39], s[2:3], 0x20
	s_nop 0
	s_load_dwordx2 s[2:3], s[2:3], 0x38
	v_lshlrev_b32_e32 v0, 2, v65
	s_waitcnt lgkmcnt(0)
	s_add_u32 s10, s36, s8
	s_addc_u32 s11, s37, s9
	s_lshl_b32 s12, s15, 8
	s_add_u32 s10, s10, s12
	s_addc_u32 s11, s11, 0
	s_add_u32 s13, s38, s8
	s_addc_u32 s15, s39, s9
	s_add_u32 s12, s13, s12
	s_addc_u32 s13, s15, 0
	global_load_dwordx4 v[26:29], v0, s[10:11] offset:48
	global_load_dwordx4 v[34:37], v0, s[10:11] offset:32
	global_load_dwordx4 v[46:49], v0, s[10:11] offset:16
	global_load_dwordx4 v[54:57], v0, s[10:11]
	global_load_dwordx4 v[30:33], v0, s[12:13] offset:48
	global_load_dwordx4 v[42:45], v0, s[12:13] offset:32
	global_load_dwordx4 v[50:53], v0, s[12:13] offset:16
	global_load_dwordx4 v[58:61], v0, s[12:13]
	v_lshlrev_b32_e32 v0, 1, v64
	v_and_b32_e32 v0, 14, v0
	s_movk_i32 s10, 0x50
	s_mov_b32 s22, 0x3b000000
	s_waitcnt vmcnt(10)
	v_pk_add_f32 v[82:83], v[66:67], v[68:69]
	v_pk_add_f32 v[84:85], v[78:79], v[80:81]
	s_nop 0
	v_pk_add_f32 v[82:83], v[82:83], v[84:85]
	v_pk_add_f32 v[84:85], v[74:75], v[76:77]
	s_nop 0
	v_pk_add_f32 v[82:83], v[82:83], v[84:85]
	v_pk_add_f32 v[84:85], v[70:71], v[72:73]
	s_nop 0
	v_pk_add_f32 v[82:83], v[82:83], v[84:85]
	s_nop 0
	v_pk_mul_f32 v[4:5], v[82:83], s[22:23] op_sel_hi:[1,0]
	s_mov_b32 s22, 0x800000
	v_fma_f32 v82, -v4, v4, v5
	v_max_f32_e32 v82, 0, v82
	v_add_f32_e32 v82, 0x358637bd, v82
	v_cmp_gt_f32_e32 vcc, s22, v82
	v_mul_f32_e32 v83, 0x4b800000, v82
	v_mov_b32_e32 v5, 0
	v_cndmask_b32_e32 v82, v82, v83, vcc
	v_rsq_f32_e32 v82, v82
	s_nop 0
	v_mul_f32_e32 v83, 0x45800000, v82
	v_cndmask_b32_e32 v63, v82, v83, vcc
	s_waitcnt vmcnt(8)
	v_lshlrev_b32_e32 v64, 16, v38
	v_sub_f32_e32 v64, v64, v4
	v_mul_f32_e32 v64, v64, v63
	v_and_b32_e32 v38, 0xffff0000, v38
	v_sub_f32_e32 v38, v38, v4
	v_mul_f32_e32 v38, v38, v63
	s_waitcnt vmcnt(0)
	v_fma_f32 v54, v54, v64, v58
	v_ashrrev_i32_e32 v64, 1, v62
	v_lshl_add_u32 v58, v65, 8, 0
	v_and_b32_e32 v65, -16, v64
	v_cvt_pk_bf16_f32 v54, v54, s0
	v_add3_u32 v65, v58, v65, v0
	ds_write_b16 v65, v54 offset:32768
	v_fma_f32 v38, v55, v38, v59
	v_bitop3_b32 v54, v64, 16, -16 bitop3:0x6c
	v_cvt_pk_bf16_f32 v38, v38, s0
	v_add3_u32 v54, v58, v54, v0
	ds_write_b16 v54, v38 offset:33024
	v_lshlrev_b32_e32 v38, 16, v39
	v_sub_f32_e32 v38, v38, v4
	v_mul_f32_e32 v38, v38, v63
	v_fma_f32 v38, v56, v38, v60
	v_bitop3_b32 v54, v64, 32, -16 bitop3:0x6c
	v_cvt_pk_bf16_f32 v38, v38, s0
	v_add3_u32 v54, v58, v54, v0
	ds_write_b16 v54, v38 offset:33280
	v_and_b32_e32 v38, 0xffff0000, v39
	v_sub_f32_e32 v38, v38, v4
	v_mul_f32_e32 v38, v38, v63
	v_fmac_f32_e32 v61, v57, v38
	v_bitop3_b32 v39, v64, 48, -16 bitop3:0x6c
	v_cvt_pk_bf16_f32 v38, v61, s0
	v_add3_u32 v39, v58, v39, v0
	ds_write_b16 v39, v38 offset:33536
	v_lshlrev_b32_e32 v38, 16, v40
	v_sub_f32_e32 v38, v38, v4
	v_mul_f32_e32 v38, v38, v63
	v_fma_f32 v38, v46, v38, v50
	v_bitop3_b32 v39, v64, 64, -16 bitop3:0x6c
	v_cvt_pk_bf16_f32 v38, v38, s0
	v_add3_u32 v39, v58, v39, v0
	ds_write_b16 v39, v38 offset:33792
	v_and_b32_e32 v38, 0xffff0000, v40
	v_sub_f32_e32 v38, v38, v4
	v_mul_f32_e32 v38, v38, v63
	v_fma_f32 v38, v47, v38, v51
	v_bitop3_b32 v39, v64, s10, -16 bitop3:0x6c
	v_cvt_pk_bf16_f32 v38, v38, s0
	v_add3_u32 v39, v58, v39, v0
	ds_write_b16 v39, v38 offset:34048
	v_lshlrev_b32_e32 v38, 16, v41
	v_sub_f32_e32 v38, v38, v4
	v_mul_f32_e32 v38, v38, v63
	s_movk_i32 s10, 0x60
	v_fma_f32 v38, v48, v38, v52
	v_bitop3_b32 v39, v64, s10, -16 bitop3:0x6c
	v_cvt_pk_bf16_f32 v38, v38, s0
	v_add3_u32 v39, v58, v39, v0
	ds_write_b16 v39, v38 offset:34304
	v_and_b32_e32 v38, 0xffff0000, v41
	v_sub_f32_e32 v38, v38, v4
	v_mul_f32_e32 v38, v38, v63
	s_movk_i32 s10, 0x70
	v_fmac_f32_e32 v53, v49, v38
	v_bitop3_b32 v39, v64, s10, -16 bitop3:0x6c
	v_cvt_pk_bf16_f32 v38, v53, s0
	v_add3_u32 v39, v58, v39, v0
	ds_write_b16 v39, v38 offset:34560
	v_lshlrev_b32_e32 v38, 16, v22
	v_sub_f32_e32 v38, v38, v4
	v_mul_f32_e32 v38, v38, v63
	v_and_b32_e32 v22, 0xffff0000, v22
	v_fma_f32 v34, v34, v38, v42
	v_bitop3_b32 v38, v64, s65, -16 bitop3:0x6c
	v_sub_f32_e32 v22, v22, v4
	v_cvt_pk_bf16_f32 v34, v34, s0
	v_add3_u32 v38, v58, v38, v0
	v_mul_f32_e32 v22, v22, v63
	s_movk_i32 s10, 0x90
	ds_write_b16 v38, v34 offset:34816
	v_fma_f32 v22, v35, v22, v43
	v_bitop3_b32 v34, v64, s10, -16 bitop3:0x6c
	v_cvt_pk_bf16_f32 v22, v22, s0
	v_add3_u32 v34, v58, v34, v0
	ds_write_b16 v34, v22 offset:35072
	v_lshlrev_b32_e32 v22, 16, v23
	v_sub_f32_e32 v22, v22, v4
	v_mul_f32_e32 v22, v22, v63
	s_movk_i32 s10, 0xa0
	v_fma_f32 v22, v36, v22, v44
	v_bitop3_b32 v34, v64, s10, -16 bitop3:0x6c
	v_cvt_pk_bf16_f32 v22, v22, s0
	v_add3_u32 v34, v58, v34, v0
	ds_write_b16 v34, v22 offset:35328
	v_and_b32_e32 v22, 0xffff0000, v23
	v_sub_f32_e32 v22, v22, v4
	v_mul_f32_e32 v22, v22, v63
	s_movk_i32 s10, 0xb0
	v_fmac_f32_e32 v45, v37, v22
	v_bitop3_b32 v23, v64, s10, -16 bitop3:0x6c
	v_cvt_pk_bf16_f32 v22, v45, s0
	v_add3_u32 v23, v58, v23, v0
	ds_write_b16 v23, v22 offset:35584
	v_lshlrev_b32_e32 v22, 16, v24
	v_sub_f32_e32 v22, v22, v4
	v_mul_f32_e32 v22, v22, v63
	s_movk_i32 s10, 0xc0
	v_fma_f32 v22, v26, v22, v30
	v_bitop3_b32 v23, v64, s10, -16 bitop3:0x6c
	v_cvt_pk_bf16_f32 v22, v22, s0
	v_add3_u32 v23, v58, v23, v0
	ds_write_b16 v23, v22 offset:35840
	v_and_b32_e32 v22, 0xffff0000, v24
	v_sub_f32_e32 v22, v22, v4
	v_mul_f32_e32 v22, v22, v63
	s_movk_i32 s10, 0xd0
	v_fma_f32 v22, v27, v22, v31
	v_bitop3_b32 v23, v64, s10, -16 bitop3:0x6c
	v_cvt_pk_bf16_f32 v22, v22, s0
	v_add3_u32 v23, v58, v23, v0
	ds_write_b16 v23, v22 offset:36096
	v_lshlrev_b32_e32 v22, 16, v25
	v_sub_f32_e32 v22, v22, v4
	v_mul_f32_e32 v22, v22, v63
	s_movk_i32 s10, 0xe0
	v_fma_f32 v22, v28, v22, v32
	v_bitop3_b32 v23, v64, s10, -16 bitop3:0x6c
	v_cvt_pk_bf16_f32 v22, v22, s0
	v_add3_u32 v23, v58, v23, v0
	ds_write_b16 v23, v22 offset:36352
	v_and_b32_e32 v22, 0xffff0000, v25
	v_sub_f32_e32 v4, v22, v4
	v_mul_f32_e32 v4, v4, v63
	s_movk_i32 s10, 0xf0
	v_fmac_f32_e32 v33, v29, v4
	v_bitop3_b32 v22, v64, s10, -16 bitop3:0x6c
	v_cvt_pk_bf16_f32 v4, v33, s0
	v_add3_u32 v0, v58, v22, v0
	ds_write_b16 v0, v4 offset:36608
	v_ashrrev_i32_e32 v0, 4, v62
	v_lshlrev_b32_e32 v4, 8, v0
	v_xor_b32_e32 v0, v0, v62
	v_lshlrev_b32_e32 v0, 4, v0
	v_and_b32_e32 v0, 0xf0, v0
	v_add3_u32 v0, 0, v0, v4
	ds_write_b128 v0, v[18:21]
	v_add_u32_e32 v0, 0x200, v62
	v_ashrrev_i32_e32 v0, 4, v0
	v_lshlrev_b32_e32 v4, 8, v0
	v_xor_b32_e32 v0, v0, v62
	v_lshlrev_b32_e32 v0, 4, v0
	v_and_b32_e32 v0, 0xf0, v0
	v_add3_u32 v0, 0, v0, v4
	ds_write_b128 v0, v[14:17]
	v_add_u32_e32 v0, 0x400, v62
	v_ashrrev_i32_e32 v0, 4, v0
	v_lshlrev_b32_e32 v4, 8, v0
	v_xor_b32_e32 v0, v0, v62
	v_lshlrev_b32_e32 v0, 4, v0
	v_and_b32_e32 v0, 0xf0, v0
	v_add3_u32 v0, 0, v0, v4
	ds_write_b128 v0, v[10:13]
	v_add_u32_e32 v0, 0x600, v62
	v_ashrrev_i32_e32 v0, 4, v0
	v_lshlrev_b32_e32 v4, 8, v0
	v_xor_b32_e32 v0, v0, v62
	v_lshlrev_b32_e32 v0, 4, v0
	v_readfirstlane_b32 s10, v62
	v_and_b32_e32 v0, 0xf0, v0
	s_ashr_i32 s10, s10, 2
	v_add3_u32 v0, 0, v0, v4
	v_bfi_b32 v30, -16, s10, v62
	ds_write_b128 v0, v[6:9]
	v_add_u32_e32 v0, s5, v30
	s_or_b32 s5, s34, s6
	v_add_u32_e32 v6, s5, v30
	v_ashrrev_i32_e32 v7, 31, v6
	v_bfe_u32 v19, v62, 4, 2
	v_lshl_add_u64 v[6:7], v[6:7], 2, s[2:3]
	v_mad_i64_i32 v[2:3], s[2:3], v0, s49, v[2:3]
	v_lshl_add_u64 v[2:3], v[2:3], 0, s[34:35]
	v_lshlrev_b32_e32 v0, 3, v19
	v_lshl_add_u64 v[20:21], v[2:3], 0, v[0:1]
	global_load_dword v18, v[6:7], off
	global_load_dwordx2 v[28:29], v[20:21], off
	global_load_dwordx2 v[26:27], v[20:21], off offset:32
	global_load_dwordx2 v[24:25], v[20:21], off offset:64
	global_load_dwordx2 v[22:23], v[20:21], off offset:96
	s_or_b32 s2, s10, 15
	s_cmpk_lt_i32 s2, 0xffe1
	v_mov_b32_e32 v4, 0
	v_mov_b32_e32 v3, 0
	v_mov_b32_e32 v2, 0
	v_mov_b32_e32 v9, 0
	v_mov_b32_e32 v8, 0
	v_mov_b32_e32 v7, 0
	v_mov_b32_e32 v6, 0
	v_mov_b32_e32 v13, 0
	v_mov_b32_e32 v12, 0
	v_mov_b32_e32 v11, 0
	v_mov_b32_e32 v10, 0
	v_mov_b32_e32 v17, 0
	v_mov_b32_e32 v16, 0
	v_mov_b32_e32 v15, 0
	v_mov_b32_e32 v14, 0
	s_waitcnt lgkmcnt(0)
	s_barrier
	s_cbranch_scc1 .LBB0_451
	s_ashr_i32 s3, s2, 31
	s_lshr_b32 s3, s3, 27
	s_add_i32 s2, s2, s3
	v_and_b32_e32 v0, 15, v62
	s_ashr_i32 s2, s2, 5
	v_mov_b32_e32 v2, 0
	v_lshl_add_u32 v30, v30, 8, 0
	v_lshl_add_u32 v31, v0, 8, 0
	s_add_i32 s2, s2, 1
	v_mov_b32_e32 v3, v2
	v_mov_b32_e32 v4, v2
	v_mov_b32_e32 v5, v2
	v_mov_b32_e32 v6, v2
	v_mov_b32_e32 v7, v2
	v_mov_b32_e32 v8, v2
	v_mov_b32_e32 v9, v2
	v_mov_b32_e32 v10, v2
	v_mov_b32_e32 v11, v2
	v_mov_b32_e32 v12, v2
	v_mov_b32_e32 v13, v2
	v_mov_b32_e32 v14, v2
	v_mov_b32_e32 v15, v2
	v_mov_b32_e32 v16, v2
	v_mov_b32_e32 v17, v2
